# attention tile-loop top and far-path branch targets aligned to 64 bytes (instruction-fetch alignment of hot branch targets)
# baseline (speedup 1.0000x reference)
; template <bool FIXED> __device__ __forceinline__ void attn_unit(int b, int h, int qb, const bf16* __restrict__ P, bf16* __restrict__ MIX, const float* __restrict__ BT, const float* __restrict__ subg, ...
;     ...
;   DMA_TILE(0, 0); DMA_TILE(1, 1);
; __global__ void __launch_bounds__(NWAVES * 64, 2) hybrid_fwd(Args args) {
;     ...
;                     float bm = fmaxf(fmaxf(BT[hh * 768 + 128 + lane], BT[hh * 768 + 128 + 64 + lane]), fmaxf(BT[hh * 768 + 384 + 128 + lane], BT[hh * 768 + 384 + 128 + 64 + lane]));
; #pragma unroll
;                     for (int o = 1; o < 64; o <<= 1) bm = fmaxf(bm, __shfl_xor(bm, o));
;                     const float sref = 11.8f * gqk + bm + 0.25f;
;                     if (sref <= 40.f) att::attn_unit<true>(bh / NH, hh, qb, (const att::bf16*)PROJ, (att::bf16*)MIX, BT, args.in[z + 10] + ll * 128, lam, 1.0f - lam_init, sref, args.in[z + 3] + (size_t)ll * 3 * CONVW, pr * 8 + half * 4, (char*)lds);
.Lmy_t0_3:
	s_add_i32 m0, s99, 0
	v_lshl_add_u64 v[80:81], s[88:89], 0, v[80:81]
	global_load_lds_dwordx4 v[80:81], off
	v_lshl_add_u64 v[80:81], s[90:91], 0, v[84:85]
	s_mov_b32 m0, s8
	v_mov_b32_e32 v83, v145
	global_load_lds_dwordx4 v[80:81], off
	v_lshl_add_u64 v[80:81], s[88:89], 0, v[86:87]
	s_add_i32 m0, s99, 0x400
	s_nop 0
	global_load_lds_dwordx4 v[80:81], off
	v_lshl_add_u64 v[80:81], v[82:83], 1, s[90:91]
	s_add_i32 m0, s99, 0x4400
	s_nop 0
	global_load_lds_dwordx4 v[80:81], off
	s_waitcnt vmcnt(14)
	v_max_f32_e32 v0, v0, v0
	s_waitcnt vmcnt(13)
	v_max_f32_e32 v1, v1, v1
	v_max_f32_e32 v0, v1, v0
	s_waitcnt vmcnt(11)
	v_max3_f32 v0, v2, v3, v0
	ds_bpermute_b32 v1, v135, v0
	s_waitcnt lgkmcnt(0)
	v_max_f32_e32 v1, v1, v1
	v_max_f32_e32 v0, v0, v1
	ds_bpermute_b32 v1, v142, v0
	s_waitcnt lgkmcnt(0)
	v_max_f32_e32 v1, v1, v1
	v_max_f32_e32 v0, v0, v1
	ds_bpermute_b32 v1, v143, v0
	s_waitcnt lgkmcnt(0)
	v_max_f32_e32 v1, v1, v1
	v_max_f32_e32 v0, v0, v1
	ds_bpermute_b32 v1, v160, v0
	s_waitcnt lgkmcnt(0)
	v_max_f32_e32 v1, v1, v1
	v_max_f32_e32 v0, v0, v1
	ds_bpermute_b32 v1, v161, v0
	s_waitcnt lgkmcnt(0)
	v_max_f32_e32 v1, v1, v1
	v_max_f32_e32 v0, v0, v1
	ds_bpermute_b32 v1, v162, v0
	s_waitcnt lgkmcnt(0)
	v_max_f32_e32 v1, v1, v1
	v_max_f32_e32 v0, v0, v1
	v_add_f32_e32 v0, v164, v0
	v_add_f32_e32 v2, 0x3e800000, v0
	v_cmp_ge_f32_e32 vcc, s0, v2
	s_and_saveexec_b64 s[0:1], vcc
	s_xor_b64 s[40:41], exec, s[0:1]
	s_cbranch_execz .LBB0_341
; __device__ __forceinline__ int v_rd_base(int lane) { return ((lane & 3) << 3) | (((lane >> 2) & 3) << 6) | (((lane >> 4) & 1) << 5) | (((lane >> 5) & 1) << 8); }
; #define WAIT_BAR(N) asm volatile("s_waitcnt vmcnt(" #N ") lgkmcnt(0)\n\ts_barrier" ::: "memory")
; template <bool FIXED> __device__ __forceinline__ void attn_unit(int b, int h, int qb, const bf16* __restrict__ P, bf16* __restrict__ MIX, const float* __restrict__ BT, const float* __restrict__ subg, ...
;     ...
;   const long rowbase = (long)b * SEQ; const int q0 = qb * QB, qw0 = q0 + wq * 32;
;   float* ws = (float*)(lds + LDS_WS) + wid * 64; float* li_l = ws; float* al_l = ws + 32;
;   float* btl = (float*)(lds + LDS_BT);
;   for (int i = tid; i < 768; i += 512) btl[i] = BT[(size_t)h * 768 + i] - (FIXED ? sref : 0.f);
;   const float* bt = btl + m * 384 + 128;
;   const float c31 = BT[(size_t)h * 768 + m * 384 + 128 + 127] - (FIXED ? sref : 0.f);
;   f32x16 cfar, czero = f32x16{};
; #pragma unroll
;   for (int r = 0; r < 16; ++r) cfar[r] = FIXED ? c31 : 0.f;
;   float m_reg = -1e30f, l_reg = 0.f; f32x16 o[4] = {}; bf16x8 qr[4];
;   const bf16* Qw = P + (rowbase + qw0 + r32) * PW + h * 128 + m * 64 + hi * 8;
; #pragma unroll
;   for (int d0 = 0; d0 < 4; ++d0) qr[d0] = *reinterpret_cast<const bf16x8*>(Qw + d0 * 16);
;   const bf16* Kh = P + rowbase * PW + 1024 + h * 128; const bf16* Vh = P + rowbase * PW + 2048 + h * 128;
;   unsigned ksrc[2], vsrc[2];
; #pragma unroll
;   for (int i = 0; i < 2; ++i) { const int pk = wid * 2 + i;
;     { const int row = 4 * pk + (lane >> 4), cc = lane & 15; ksrc[i] = (unsigned)(row * PW + ((cc ^ (row & 7)) * 8)); }
;     { const int ob = pk * 1024 + lane * 16, sub = ob >> 9, kk = (sub >> 2) * 8 + ((ob & 511) >> 6), k = (kk & ~0xC) | ((kk & 4) << 1) | ((kk & 8) >> 1), c = (sub & 3) * 32 + ((ob & 63) >> 1);
;       vsrc[i] = (unsigned)(k * PW + c); } }
;   typedef __attribute__((address_space(3))) unsigned lds_u32;
;   typedef __attribute__((address_space(3))) unsigned char lds_u8;
;   lds_u8* const ring = (lds_u8*)lds + wid * 2048;
;     ...
;   const lds_cptr vp0 = (lds_cptr)lds + SHM_K + v_rd_base(lane);
;     ...
;   f32x16 p0, p1; float al, ca; bf16x8 pa0, pa1, pa2, pa3; const int NT = 2 * qb + 2;
;     ...
;   const int NTT = ATT_REP * NT;
;   DMA_TILE(0, 0); DMA_TILE(1, 1);
;   WAIT_BAR(4);
	v_mov_b32_e32 v0, v169
	s_nop 0
	v_readfirstlane_b32 s25, v0
	s_waitcnt vmcnt(8)
	v_sub_f32_e32 v102, v102, v2
	v_add_u32_e32 v101, s2, v100
	ds_write_b32 v101, v102
	v_cmp_gt_u32_e32 vcc, 0x100, v169
	s_and_saveexec_b64 s[0:1], vcc
	v_sub_f32_e32 v103, v103, v2
	ds_write_b32 v101, v103 offset:2048
	s_mov_b64 exec, s[0:1]
	s_ashr_i32 s1, s25, 6
	s_ashr_i32 s26, s25, 8
	s_and_b32 s24, s1, 3
	s_mul_i32 s6, s26, 0x180
	s_lshl_b32 s0, s24, 5
	s_ashr_i32 s7, s6, 31
	s_or_b32 s29, s0, s34
	s_lshl_b64 s[6:7], s[6:7], 2
	s_add_u32 s6, s10, s6
	s_addc_u32 s7, s11, s7
	v_and_b32_e32 v134, 31, v0
	s_or_b32 s22, s54, s29
	v_bfe_u32 v167, v0, 5, 1
	v_lshlrev_b32_e32 v144, 4, v167
	s_lshl_b32 s8, s1, 3
	v_bfe_u32 v13, v0, 2, 2
	v_and_b32_e32 v168, 63, v0
	v_lshlrev_b32_e32 v166, 3, v168
	v_bfe_u32 v12, v0, 4, 2
	v_and_b32_e32 v15, 32, v0
	v_and_b32_e32 v16, 24, v166
	v_lshlrev_b32_e32 v19, 4, v0
	v_mov_b32_e32 v9, v145
	v_mov_b32_e32 v5, v145
	v_mov_b32_e32 v7, v145
	s_add_i32 s0, s34, s0
	s_lshl_b32 s38, s73, 9
	v_mov_b32_e32 v176, 0
	s_mov_b32 s23, s55
	s_lshl_b32 s28, s73, 1
	s_addk_i32 s29, 0xff51
	v_lshlrev_b32_e32 v171, 8, v134
	s_addk_i32 s38, 0x200
	s_mov_b32 s39, 0
	s_mov_b32 s44, 0
	s_mov_b32 s45, 0
	s_cmp_lg_u64 s[30:31], 0
	s_cselect_b32 s45, 0, 2
	s_mov_b32 s56, 0
	v_mov_b32_e32 v22, v176
	v_mov_b32_e32 v23, v176
	v_mov_b32_e32 v24, v176
	v_mov_b32_e32 v25, v176
	v_mov_b32_e32 v26, v176
	v_mov_b32_e32 v27, v176
	v_mov_b32_e32 v28, v176
	v_mov_b32_e32 v29, v176
	v_mov_b32_e32 v30, v176
	v_mov_b32_e32 v31, v176
	v_mov_b32_e32 v32, 0
	v_mov_b32_e32 v33, v176
	v_mov_b32_e32 v34, v176
	v_mov_b32_e32 v35, v176
	v_mov_b32_e32 v36, v176
	v_mov_b32_e32 v37, v176
	v_mov_b32_e32 v38, v176
	v_mov_b32_e32 v39, v176
	v_mov_b32_e32 v40, v176
	v_mov_b32_e32 v41, v176
	v_mov_b32_e32 v42, v176
	v_mov_b32_e32 v43, v176
	v_mov_b32_e32 v44, v176
	v_mov_b32_e32 v45, v176
	v_mov_b32_e32 v46, v176
	v_mov_b32_e32 v47, v176
	v_mov_b32_e32 v48, 0
	v_mov_b32_e32 v49, v176
	v_mov_b32_e32 v50, v176
	v_mov_b32_e32 v51, v176
	v_mov_b32_e32 v52, v176
	v_mov_b32_e32 v53, v176
	v_mov_b32_e32 v54, v176
	v_mov_b32_e32 v55, v176
	v_mov_b32_e32 v56, v176
	v_mov_b32_e32 v57, v176
	v_mov_b32_e32 v58, v176
	v_mov_b32_e32 v59, v176
	v_mov_b32_e32 v60, v176
	v_mov_b32_e32 v61, v176
	v_mov_b32_e32 v62, v176
	v_mov_b32_e32 v63, v176
	s_waitcnt vmcnt(8)
	v_sub_f32_e32 v64, v104, v2
	v_or_b32_e32 v1, s22, v134
	v_mov_b64_e32 v[2:3], s[16:17]
	v_mad_u64_u32 v[2:3], s[6:7], v1, s70, v[2:3]
	s_lshl_b32 s6, s26, 6
	v_mad_i32_i24 v3, s55, v196, v3
	s_ashr_i32 s7, s6, 31
	v_lshl_add_u64 v[2:3], s[6:7], 1, v[2:3]
	v_lshl_add_u64 v[2:3], v[2:3], 0, v[144:145]
	v_lshrrev_b32_e32 v2, 2, v0
	s_and_b32 s6, s8, -16
	v_and_b32_e32 v14, 4, v2
	s_lshl_b32 s7, s1, 3
	s_and_b32 s7, s7, 8
	v_or3_b32 v2, v14, v13, s6
	v_or_b32_e32 v2, s7, v2
	v_mul_lo_u32 v2, v2, s35
	v_or3_b32 v4, v2, v15, v16
	v_or_b32_e32 v2, s8, v12
	v_bitop3_b32 v3, v12, v0, 15 bitop3:0x78
	v_and_b32_e32 v1, 15, v0
	v_mul_lo_u32 v2, v2, s35
	v_lshlrev_b32_e32 v17, 3, v3
	v_or_b32_e32 v8, v2, v17
	v_or_b32_e32 v2, 4, v12
	v_bitop3_b32 v1, v12, v1, 4 bitop3:0x36
	v_or_b32_e32 v2, s8, v2
	v_lshlrev_b32_e32 v18, 3, v1
	v_and_b32_e32 v1, 0xc0, v19
	v_lshlrev_b32_e32 v0, 1, v0
	v_mul_lo_u32 v2, v2, s35
	s_lshl_b32 s8, s1, 11
	v_and_b32_e32 v20, 32, v0
	v_add3_u32 v21, 0, v16, v1
	v_lshlrev_b64 v[0:1], 1, v[8:9]
	v_or_b32_e32 v6, v2, v18
	s_add_i32 s27, s8, 0
	v_lshl_add_u64 v[8:9], s[18:19], 0, v[0:1]
	v_or_b32_e32 v2, 64, v4
	s_add_i32 s8, s27, 0x4000
	v_lshl_add_u64 v[8:9], v[8:9], 0, s[36:37]
	s_mov_b32 m0, s27
	v_lshlrev_b64 v[4:5], 1, v[4:5]
	v_lshlrev_b64 v[6:7], 1, v[6:7]
	v_lshl_add_u64 v[8:9], s[20:21], 0, v[4:5]
	s_mov_b32 m0, s8
	v_lshl_add_u64 v[10:11], s[18:19], 0, v[6:7]
	v_lshl_add_u64 v[10:11], v[10:11], 0, s[36:37]
	s_add_i32 m0, s27, 0x400
	v_lshl_add_u64 v[8:9], v[8:9], 0, s[94:95]
	s_add_i32 m0, s27, 0x4400
	s_add_i32 s8, s27, 0xc000
	s_add_i32 m0, s27, 0x8000
	v_lshl_add_u64 v[0:1], s[88:89], 0, v[0:1]
	v_lshl_add_u64 v[0:1], s[90:91], 0, v[4:5]
	s_mov_b32 m0, s8
	v_mov_b32_e32 v3, v145
	v_lshl_add_u64 v[0:1], s[88:89], 0, v[6:7]
	s_add_i32 m0, s27, 0x8400
	s_lshl_b32 s8, s26, 7
	v_lshl_add_u64 v[0:1], v[2:3], 1, s[90:91]
	s_add_i32 m0, s27, 0xc400
	s_mul_i32 s1, s1, 0xc000
	v_or_b32_e32 v0, s8, v144
	v_and_b32_e32 v1, 0x70, v19
	v_bitop3_b32 v173, v0, v1, 32 bitop3:0x36
	v_bitop3_b32 v174, v0, v1, 64 bitop3:0x36
	v_bitop3_b32 v175, v0, v1, s64 bitop3:0x36
	v_or_b32_e32 v0, s6, v14
	v_or3_b32 v0, v0, s7, v13
	v_mul_lo_u32 v0, v0, s35
	v_bitop3_b32 v172, s8, v1, v144 bitop3:0x36
	v_add_u32_e32 v172, v172, v171
	v_add_u32_e32 v173, v173, v171
	v_add_u32_e32 v174, v174, v171
	v_add_u32_e32 v175, v175, v171
	v_or3_b32 v0, v0, v15, v16
	v_mov_b32_e32 v1, v145
	s_add_i32 s6, s1, 0x6000
	v_lshlrev_b64 v[136:137], 1, v[0:1]
	v_mov_b32_e32 v0, s6
	v_mad_u32_u24 v0, v12, s35, v0
	v_or_b32_e32 v0, v0, v18
	v_lshlrev_b32_e32 v138, 1, v0
	v_mov_b32_e32 v0, s1
	v_mad_u32_u24 v0, v12, s35, v0
	v_or_b32_e32 v0, v0, v17
	s_waitcnt vmcnt(4) lgkmcnt(0)
	s_barrier
	v_lshlrev_b32_e32 v2, 2, v167
	v_lshlrev_b32_e32 v140, 1, v0
	s_mul_i32 s1, s26, 0x600
	v_add_u32_e32 v0, s0, v134
	v_and_b32_e32 v8, 0x100, v166
	v_sub_u32_e32 v0, v0, v2
	s_add_i32 s0, s1, 0
	v_mov_b32_e32 v65, v64
	v_mov_b32_e32 v66, v64
	v_mov_b32_e32 v67, v64
	v_mov_b32_e32 v68, v64
	v_mov_b32_e32 v69, v64
	v_mov_b32_e32 v70, v64
	v_mov_b32_e32 v71, v64
	v_mov_b32_e32 v72, v64
	v_mov_b32_e32 v73, v64
	v_mov_b32_e32 v74, v64
	v_mov_b32_e32 v75, v64
	v_mov_b32_e32 v76, v64
	v_mov_b32_e32 v77, v64
	v_mov_b32_e32 v78, v64
	v_mov_b32_e32 v79, v64
	v_add3_u32 v170, v21, v20, v8
	v_lshl_add_u32 v178, v0, 2, s0
	s_mov_b64 s[0:1], s[92:93]
	v_mov_b32_e32 v0, 0
	v_mov_b32_e32 v1, v176
	v_mov_b32_e32 v2, v176
	v_mov_b32_e32 v3, v176
	v_mov_b32_e32 v4, v176
	v_mov_b32_e32 v5, v176
	v_mov_b32_e32 v6, v176
	v_mov_b32_e32 v7, v176
	v_mov_b32_e32 v8, v176
	v_mov_b32_e32 v9, v176
	v_mov_b32_e32 v10, v176
	v_mov_b32_e32 v11, v176
	v_mov_b32_e32 v12, v176
	v_mov_b32_e32 v13, v176
	v_mov_b32_e32 v14, v176
	v_mov_b32_e32 v15, v176
	v_mov_b32_e32 v16, 0
	v_mov_b32_e32 v17, v176
	v_mov_b32_e32 v18, v176
	v_mov_b32_e32 v19, v176
	v_mov_b32_e32 v20, v176
	v_mov_b32_e32 v21, v176
	s_lshl_b32 s59, s45, 15
	s_add_i32 s9, s59, 0xffff8000
	s_cmp_gt_i32 s45, 0
	s_cselect_b32 s9, s9, 0x10000
	s_add_i32 s9, s27, s9
	s_add_u32 s98, s0, 0x1a380800
	s_addc_u32 s99, s1, 0
	s_add_u32 s100, s0, s4
	s_addc_u32 s101, s1, s5
	s_waitcnt vmcnt(4)
	s_branch .LBB0_312
	.p2align 6

; #define SBAR() __builtin_amdgcn_sched_barrier(0)
; __device__ __forceinline__ void qkt(f32x16& p0, f32x16& p1, const char* Ks, const bf16x8* qr, int r32, int hi, int m, const f32x16& cinit) {
;   bf16x8 kf[8];
; #pragma unroll
;   for (int d0 = 0; d0 < 4; ++d0) { const int cb = (m * 64 + d0 * 16 + hi * 8) * 2;
;     kf[2 * d0] = *reinterpret_cast<const bf16x8*>(Ks + KSWZ(r32, cb)); kf[2 * d0 + 1] = *reinterpret_cast<const bf16x8*>(Ks + KSWZ(32 + r32, cb)); }
;   SBAR();
;   p0 = __builtin_amdgcn_mfma_f32_32x32x16_bf16(kf[0], qr[0], cinit, 0, 0, 0);
;   p1 = __builtin_amdgcn_mfma_f32_32x32x16_bf16(kf[1], qr[0], cinit, 0, 0, 0);
; #pragma unroll
;   for (int d0 = 1; d0 < 4; ++d0) {
;     p0 = __builtin_amdgcn_mfma_f32_32x32x16_bf16(kf[2 * d0], qr[d0], p0, 0, 0, 0);
;     p1 = __builtin_amdgcn_mfma_f32_32x32x16_bf16(kf[2 * d0 + 1], qr[d0], p1, 0, 0, 0); }
;   SBAR();
; }
; __device__ __forceinline__ void bias_mask(f32x16& p0, f32x16& p1, const float* bt, int base) {
; #pragma unroll
;   for (int r = 0; r < 16; ++r) { const int c = (r & 3) + 8 * (r >> 2); p0[r] += bt[base - c]; }
;   SBAR();
; #pragma unroll
;   for (int r = 0; r < 16; ++r) { const int c = (r & 3) + 8 * (r >> 2); p1[r] += bt[base - c - 32]; }
; }
.LBB0_316:
	s_cmp_ge_i32 s39, s29
	s_cbranch_scc0 .Ledge_far
	v_add_u32_e32 v85, s59, v172
	v_add_u32_e32 v87, s59, v173
	v_add_u32_e32 v89, s59, v174
	v_add_u32_e32 v91, s59, v175
	ds_read_b128 v[80:83], v85
	ds_read_b128 v[96:99], v85 offset:8192
	ds_read_b128 v[198:201], v87
	ds_read_b128 v[202:205], v87 offset:8192
	ds_read_b128 v[206:209], v89
	ds_read_b128 v[210:213], v89 offset:8192
	ds_read_b128 v[214:217], v91
	ds_read_b128 v[218:221], v91 offset:8192
	v_add_u32_e32 v230, s44, v178
	v_add_u32_e32 v230, 0x18914, v230
	s_waitcnt lgkmcnt(0)
	v_mfma_f32_32x32x16_bf16 v[80:95], v[80:83], v[112:115], 0
	v_mfma_f32_32x32x16_bf16 v[96:111], v[96:99], v[112:115], 0
	v_mfma_f32_32x32x16_bf16 v[80:95], v[198:201], v[116:119], v[80:95]
	v_mfma_f32_32x32x16_bf16 v[96:111], v[202:205], v[116:119], v[96:111]
	v_mfma_f32_32x32x16_bf16 v[80:95], v[206:209], v[120:123], v[80:95]
	v_mfma_f32_32x32x16_bf16 v[96:111], v[210:213], v[120:123], v[96:111]
	v_mfma_f32_32x32x16_bf16 v[80:95], v[214:217], v[124:127], v[80:95]
	v_mfma_f32_32x32x16_bf16 v[96:111], v[218:221], v[124:127], v[96:111]
	ds_read2_b32 v[198:199], v230 offset0:58 offset1:59
	ds_read2_b32 v[200:201], v230 offset0:56 offset1:57
	ds_read2_b32 v[202:203], v230 offset0:50 offset1:51
	ds_read2_b32 v[204:205], v230 offset0:48 offset1:49
	ds_read2_b32 v[206:207], v230 offset0:42 offset1:43
	ds_read2_b32 v[208:209], v230 offset0:40 offset1:41
	ds_read2_b32 v[210:211], v230 offset0:34 offset1:35
	ds_read2_b32 v[212:213], v230 offset0:32 offset1:33
	ds_read2_b32 v[214:215], v230 offset0:26 offset1:27
	ds_read2_b32 v[216:217], v230 offset0:24 offset1:25
	ds_read2_b32 v[218:219], v230 offset0:18 offset1:19
	ds_read2_b32 v[220:221], v230 offset0:16 offset1:17
	ds_read2_b32 v[222:223], v230 offset0:10 offset1:11
	ds_read2_b32 v[224:225], v230 offset0:8 offset1:9
	ds_read2_b32 v[226:227], v230 offset0:2 offset1:3
	ds_read2_b32 v[228:229], v230 offset0:0 offset1:1
	s_waitcnt lgkmcnt(0)
	v_add_f32_e32 v80, v80, v199
	v_add_f32_e32 v81, v81, v198
	v_pk_add_f32 v[82:83], v[82:83], v[200:201] op_sel:[0,1] op_sel_hi:[1,0]
	v_pk_add_f32 v[84:85], v[84:85], v[202:203] op_sel:[0,1] op_sel_hi:[1,0]
	v_pk_add_f32 v[86:87], v[86:87], v[204:205] op_sel:[0,1] op_sel_hi:[1,0]
	v_pk_add_f32 v[88:89], v[88:89], v[206:207] op_sel:[0,1] op_sel_hi:[1,0]
	v_pk_add_f32 v[90:91], v[90:91], v[208:209] op_sel:[0,1] op_sel_hi:[1,0]
	v_pk_add_f32 v[92:93], v[92:93], v[210:211] op_sel:[0,1] op_sel_hi:[1,0]
	v_pk_add_f32 v[94:95], v[94:95], v[212:213] op_sel:[0,1] op_sel_hi:[1,0]
	v_pk_add_f32 v[96:97], v[96:97], v[214:215] op_sel:[0,1] op_sel_hi:[1,0]
	v_pk_add_f32 v[98:99], v[98:99], v[216:217] op_sel:[0,1] op_sel_hi:[1,0]
	v_pk_add_f32 v[100:101], v[100:101], v[218:219] op_sel:[0,1] op_sel_hi:[1,0]
	v_pk_add_f32 v[102:103], v[102:103], v[220:221] op_sel:[0,1] op_sel_hi:[1,0]
	v_pk_add_f32 v[104:105], v[104:105], v[222:223] op_sel:[0,1] op_sel_hi:[1,0]
	v_pk_add_f32 v[106:107], v[106:107], v[224:225] op_sel:[0,1] op_sel_hi:[1,0]
	v_pk_add_f32 v[108:109], v[108:109], v[226:227] op_sel:[0,1] op_sel_hi:[1,0]
	v_pk_add_f32 v[110:111], v[110:111], v[228:229] op_sel:[0,1] op_sel_hi:[1,0]
	s_branch .LBB0_320
	.p2align 6
